# accumulator zeroing per GEMM tile via 64-bit moves (P1/P5/P7 or P6)
# speedup vs baseline: 1.0464x; 1.0051x over previous
; template <class Epi>
; __device__ __forceinline__ void gemm_tile(const u16* __restrict__ A, const u16* __restrict__ Bt, int K,
;                                           int brow, int bcol, bool first, bool has_next, int nbrow, int nbcol, Epi epi) {
;     ...
;   const int tidx = opaque_tid(epi.p);
;   int wid = tidx >> 6, lane = tidx & 63, wr = wid >> 2, wc = wid & 3, fr = lane & 15, fq = lane >> 4;
;   unsigned voff0, voff1;
;   { int _r, _c; stage_rc(tidx * 16, _r, _c); voff0 = (unsigned)(_r * K + _c) * 2u;
;     stage_rc(tidx * 16 + 8192, _r, _c); voff1 = (unsigned)(_r * K + _c) * 2u; }
;   f32x4 acc[2][2][4][2] = {};
;   bf16x8 At[4][2], B0[2][2], B1[2][2];
;   int nt = K / BK;
;   if (first) {
;     STAGE(SB(0, 0), Bt, bcol, 0); STAGE(SA(0, 0), A, brow, 0);
.LBB0_142:
	v_and_b32_e32 v2, 15, v0
	v_lshlrev_b32_e32 v4, 2, v0
	v_and_b32_e32 v3, 48, v0
	v_lshlrev_b32_e32 v2, 6, v2
	v_and_b32_e32 v4, 32, v4
	v_lshlrev_b32_e32 v0, 6, v0
	s_movk_i32 s6, 0x3c0
	v_bitop3_b32 v2, v2, v4, v3 bitop3:0x36
	v_lshlrev_b32_e32 v9, 6, v152
	v_lshlrev_b32_e32 v1, 13, v1
	v_and_or_b32 v0, v0, s6, v3
	v_add_u32_e32 v5, s82, v2
	v_add_u32_e32 v6, s83, v2
	v_add_u32_e32 v7, s84, v2
	v_add_u32_e32 v8, s85, v2
	v_and_b32_e32 v9, 0x3000, v9
	v_add_u32_e32 v2, 16, v2
	v_xad_u32 v3, v0, v4, 16
	v_or_b32_e32 v4, 0x800, v1
	v_or_b32_e32 v10, 0x1000, v1
	v_or_b32_e32 v11, 0x1800, v1
	v_mov_b32_e32 v0, 0
	s_mov_b32 s44, -2
	v_add_u32_e32 v150, v5, v9
	v_add_u32_e32 v162, v2, v1
	v_add_u32_e32 v161, v3, v4
	v_add_u32_e32 v160, v3, v10
	v_add_u32_e32 v159, v3, v11
	v_add_u32_e32 v149, v6, v9
	v_add_u32_e32 v148, v7, v9
	v_add_u32_e32 v147, v8, v9
	s_mov_b64 s[6:7], s[34:35]
	v_mov_b32_e32 v1, v0
	v_mov_b64_e32 v[2:3], v[0:1]
	v_mov_b64_e32 v[4:5], v[0:1]
	v_mov_b64_e32 v[6:7], v[0:1]
	v_mov_b64_e32 v[8:9], v[0:1]
	v_mov_b64_e32 v[10:11], v[0:1]
	v_mov_b64_e32 v[12:13], v[0:1]
	v_mov_b64_e32 v[14:15], v[0:1]
	v_mov_b64_e32 v[16:17], v[0:1]
	v_mov_b64_e32 v[18:19], v[0:1]
	v_mov_b64_e32 v[20:21], v[0:1]
	v_mov_b64_e32 v[22:23], v[0:1]
	v_mov_b64_e32 v[24:25], v[0:1]
	v_mov_b64_e32 v[26:27], v[0:1]
	v_mov_b64_e32 v[28:29], v[0:1]
	v_mov_b64_e32 v[30:31], v[0:1]
	v_mov_b64_e32 v[32:33], v[0:1]
	v_mov_b64_e32 v[34:35], v[0:1]
	v_mov_b64_e32 v[36:37], v[0:1]
	v_mov_b64_e32 v[38:39], v[0:1]
	v_mov_b64_e32 v[40:41], v[0:1]
	v_mov_b64_e32 v[42:43], v[0:1]
	v_mov_b64_e32 v[44:45], v[0:1]
	v_mov_b64_e32 v[46:47], v[0:1]
	v_mov_b64_e32 v[48:49], v[0:1]
	v_mov_b64_e32 v[50:51], v[0:1]
	v_mov_b64_e32 v[52:53], v[0:1]
	v_mov_b64_e32 v[54:55], v[0:1]
	v_mov_b64_e32 v[56:57], v[0:1]
	v_mov_b64_e32 v[58:59], v[0:1]
	v_mov_b64_e32 v[60:61], v[0:1]
	v_mov_b64_e32 v[62:63], v[0:1]
	v_mov_b64_e32 v[64:65], v[0:1]
	v_mov_b64_e32 v[66:67], v[0:1]
	v_mov_b64_e32 v[68:69], v[0:1]
	v_mov_b64_e32 v[70:71], v[0:1]
	v_mov_b64_e32 v[72:73], v[0:1]
	v_mov_b64_e32 v[74:75], v[0:1]
	v_mov_b64_e32 v[76:77], v[0:1]
	v_mov_b64_e32 v[78:79], v[0:1]
	v_mov_b64_e32 v[80:81], v[0:1]
	v_mov_b64_e32 v[82:83], v[0:1]
	v_mov_b64_e32 v[84:85], v[0:1]
	v_mov_b64_e32 v[86:87], v[0:1]
	v_mov_b64_e32 v[88:89], v[0:1]
	v_mov_b64_e32 v[90:91], v[0:1]
	v_mov_b64_e32 v[92:93], v[0:1]
	v_mov_b64_e32 v[94:95], v[0:1]
	v_mov_b64_e32 v[96:97], v[0:1]
	v_mov_b64_e32 v[98:99], v[0:1]
	v_mov_b64_e32 v[100:101], v[0:1]
	v_mov_b64_e32 v[102:103], v[0:1]
	v_mov_b64_e32 v[104:105], v[0:1]
	v_mov_b64_e32 v[106:107], v[0:1]
	v_mov_b64_e32 v[108:109], v[0:1]
	v_mov_b64_e32 v[110:111], v[0:1]
	v_mov_b64_e32 v[112:113], v[0:1]
	v_mov_b64_e32 v[114:115], v[0:1]
	v_mov_b64_e32 v[116:117], v[0:1]
	v_mov_b64_e32 v[118:119], v[0:1]
	v_mov_b64_e32 v[120:121], v[0:1]
	v_mov_b64_e32 v[122:123], v[0:1]
	v_mov_b64_e32 v[124:125], v[0:1]
	v_mov_b64_e32 v[126:127], v[0:1]
	v_lshl_add_u64 v[128:129], v[164:165], 0, s[8:9]
	v_lshl_add_u64 v[130:131], v[132:133], 0, s[8:9]
	v_lshl_add_u64 v[134:135], v[164:165], 0, s[10:11]
	v_lshl_add_u64 v[136:137], v[132:133], 0, s[10:11]
	v_lshl_add_u64 v[138:139], v[164:165], 0, s[64:65]
	v_lshl_add_u64 v[140:141], v[132:133], 0, s[64:65]
	v_lshl_add_u64 v[142:143], v[164:165], 0, s[4:5]
	v_lshl_add_u64 v[144:145], v[132:133], 0, s[4:5]

; template <class Epi>
; __device__ __forceinline__ void gemm_tile(const u16* __restrict__ A, const u16* __restrict__ Bt, int K,
;                                           int brow, int bcol, bool first, bool has_next, int nbrow, int nbcol, Epi epi) {
;     ...
;   const int tidx = opaque_tid(epi.p);
;   int wid = tidx >> 6, lane = tidx & 63, wr = wid >> 2, wc = wid & 3, fr = lane & 15, fq = lane >> 4;
;   unsigned voff0, voff1;
;   { int _r, _c; stage_rc(tidx * 16, _r, _c); voff0 = (unsigned)(_r * K + _c) * 2u;
;     stage_rc(tidx * 16 + 8192, _r, _c); voff1 = (unsigned)(_r * K + _c) * 2u; }
;   f32x4 acc[2][2][4][2] = {};
;   bf16x8 At[4][2], B0[2][2], B1[2][2];
;   int nt = K / BK;
;   if (first) {
;     STAGE(SB(0, 0), Bt, bcol, 0); STAGE(SA(0, 0), A, brow, 0);
.LBB0_591:
	v_and_b32_e32 v2, 15, v0
	v_lshlrev_b32_e32 v4, 2, v0
	v_and_b32_e32 v3, 48, v0
	v_lshlrev_b32_e32 v2, 6, v2
	v_and_b32_e32 v4, 32, v4
	v_lshlrev_b32_e32 v0, 6, v0
	v_bitop3_b32 v2, v2, v4, v3 bitop3:0x36
	v_lshlrev_b32_e32 v9, 6, v148
	v_lshlrev_b32_e32 v1, 13, v1
	v_and_or_b32 v0, v0, s60, v3
	v_add_u32_e32 v5, s82, v2
	v_add_u32_e32 v6, s83, v2
	v_add_u32_e32 v7, s84, v2
	v_add_u32_e32 v8, s85, v2
	v_and_b32_e32 v9, 0x3000, v9
	v_add_u32_e32 v2, 16, v2
	v_xad_u32 v3, v0, v4, 16
	v_or_b32_e32 v4, 0x800, v1
	v_or_b32_e32 v10, 0x1000, v1
	v_or_b32_e32 v11, 0x1800, v1
	v_mov_b32_e32 v0, 0
	v_lshl_add_u64 v[132:133], v[128:129], 0, s[40:41]
	v_lshl_add_u64 v[134:135], v[130:131], 0, s[40:41]
	v_lshl_add_u64 v[136:137], v[128:129], 0, s[42:43]
	v_lshl_add_u64 v[138:139], v[130:131], 0, s[42:43]
	v_lshl_add_u64 v[140:141], v[128:129], 0, s[44:45]
	v_lshl_add_u64 v[142:143], v[130:131], 0, s[44:45]
	v_lshl_add_u64 v[144:145], v[128:129], 0, s[36:37]
	v_lshl_add_u64 v[146:147], v[130:131], 0, s[36:37]
	s_mov_b32 s1, -2
	v_add_u32_e32 v164, v5, v9
	v_add_u32_e32 v159, v2, v1
	v_add_u32_e32 v158, v3, v4
	v_add_u32_e32 v157, v3, v10
	v_add_u32_e32 v156, v3, v11
	v_add_u32_e32 v163, v6, v9
	v_add_u32_e32 v161, v7, v9
	v_add_u32_e32 v160, v8, v9
	s_mov_b64 s[40:41], s[34:35]
	v_mov_b32_e32 v1, v0
	v_mov_b64_e32 v[2:3], v[0:1]
	v_mov_b64_e32 v[4:5], v[0:1]
	v_mov_b64_e32 v[6:7], v[0:1]
	v_mov_b64_e32 v[8:9], v[0:1]
	v_mov_b64_e32 v[10:11], v[0:1]
	v_mov_b64_e32 v[12:13], v[0:1]
	v_mov_b64_e32 v[14:15], v[0:1]
	v_mov_b64_e32 v[16:17], v[0:1]
	v_mov_b64_e32 v[18:19], v[0:1]
	v_mov_b64_e32 v[20:21], v[0:1]
	v_mov_b64_e32 v[22:23], v[0:1]
	v_mov_b64_e32 v[24:25], v[0:1]
	v_mov_b64_e32 v[26:27], v[0:1]
	v_mov_b64_e32 v[28:29], v[0:1]
	v_mov_b64_e32 v[30:31], v[0:1]
	v_mov_b64_e32 v[32:33], v[0:1]
	v_mov_b64_e32 v[34:35], v[0:1]
	v_mov_b64_e32 v[36:37], v[0:1]
	v_mov_b64_e32 v[38:39], v[0:1]
	v_mov_b64_e32 v[40:41], v[0:1]
	v_mov_b64_e32 v[42:43], v[0:1]
	v_mov_b64_e32 v[44:45], v[0:1]
	v_mov_b64_e32 v[46:47], v[0:1]
	v_mov_b64_e32 v[48:49], v[0:1]
	v_mov_b64_e32 v[50:51], v[0:1]
	v_mov_b64_e32 v[52:53], v[0:1]
	v_mov_b64_e32 v[54:55], v[0:1]
	v_mov_b64_e32 v[56:57], v[0:1]
	v_mov_b64_e32 v[58:59], v[0:1]
	v_mov_b64_e32 v[60:61], v[0:1]
	v_mov_b64_e32 v[62:63], v[0:1]
	v_mov_b64_e32 v[64:65], v[0:1]
	v_mov_b64_e32 v[66:67], v[0:1]
	v_mov_b64_e32 v[68:69], v[0:1]
	v_mov_b64_e32 v[70:71], v[0:1]
	v_mov_b64_e32 v[72:73], v[0:1]
	v_mov_b64_e32 v[74:75], v[0:1]
	v_mov_b64_e32 v[76:77], v[0:1]
	v_mov_b64_e32 v[78:79], v[0:1]
	v_mov_b64_e32 v[80:81], v[0:1]
	v_mov_b64_e32 v[82:83], v[0:1]
	v_mov_b64_e32 v[84:85], v[0:1]
	v_mov_b64_e32 v[86:87], v[0:1]
	v_mov_b64_e32 v[88:89], v[0:1]
	v_mov_b64_e32 v[90:91], v[0:1]
	v_mov_b64_e32 v[92:93], v[0:1]
	v_mov_b64_e32 v[94:95], v[0:1]
	v_mov_b64_e32 v[96:97], v[0:1]
	v_mov_b64_e32 v[98:99], v[0:1]
	v_mov_b64_e32 v[100:101], v[0:1]
	v_mov_b64_e32 v[102:103], v[0:1]
	v_mov_b64_e32 v[104:105], v[0:1]
	v_mov_b64_e32 v[106:107], v[0:1]
	v_mov_b64_e32 v[108:109], v[0:1]
	v_mov_b64_e32 v[110:111], v[0:1]
	v_mov_b64_e32 v[112:113], v[0:1]
	v_mov_b64_e32 v[114:115], v[0:1]
	v_mov_b64_e32 v[116:117], v[0:1]
	v_mov_b64_e32 v[118:119], v[0:1]
	v_mov_b64_e32 v[120:121], v[0:1]
	v_mov_b64_e32 v[122:123], v[0:1]
	v_mov_b64_e32 v[124:125], v[0:1]
	v_mov_b64_e32 v[126:127], v[0:1]

; template <class Epi>
; __device__ __forceinline__ void gemm_tile(const u16* __restrict__ A, const u16* __restrict__ Bt, int K,
;                                           int brow, int bcol, bool first, bool has_next, int nbrow, int nbcol, Epi epi) {
;     ...
;   const int tidx = opaque_tid(epi.p);
;   int wid = tidx >> 6, lane = tidx & 63, wr = wid >> 2, wc = wid & 3, fr = lane & 15, fq = lane >> 4;
;   unsigned voff0, voff1;
;   { int _r, _c; stage_rc(tidx * 16, _r, _c); voff0 = (unsigned)(_r * K + _c) * 2u;
;     stage_rc(tidx * 16 + 8192, _r, _c); voff1 = (unsigned)(_r * K + _c) * 2u; }
;   f32x4 acc[2][2][4][2] = {};
;   bf16x8 At[4][2], B0[2][2], B1[2][2];
;   int nt = K / BK;
;   if (first) {
;     STAGE(SB(0, 0), Bt, bcol, 0); STAGE(SA(0, 0), A, brow, 0);
.LBB0_662:
	v_and_b32_e32 v2, 15, v0
	v_lshlrev_b32_e32 v4, 2, v0
	v_and_b32_e32 v3, 48, v0
	v_lshlrev_b32_e32 v2, 6, v2
	v_and_b32_e32 v4, 32, v4
	v_lshlrev_b32_e32 v0, 6, v0
	v_bitop3_b32 v2, v2, v4, v3 bitop3:0x36
	v_lshlrev_b32_e32 v9, 6, v129
	v_lshlrev_b32_e32 v1, 13, v1
	v_and_or_b32 v0, v0, s41, v3
	v_add_u32_e32 v5, s82, v2
	v_add_u32_e32 v6, s83, v2
	v_add_u32_e32 v7, s84, v2
	v_add_u32_e32 v8, s85, v2
	v_and_b32_e32 v9, 0x3000, v9
	v_add_u32_e32 v2, 16, v2
	v_xad_u32 v3, v0, v4, 16
	v_or_b32_e32 v4, 0x800, v1
	v_or_b32_e32 v10, 0x1000, v1
	v_or_b32_e32 v11, 0x1800, v1
	v_mov_b32_e32 v0, 0
	v_lshl_add_u64 v[136:137], s[20:21], 0, v[132:133]
	v_lshl_add_u64 v[138:139], s[20:21], 0, v[134:135]
	v_lshl_add_u64 v[140:141], v[132:133], 0, s[18:19]
	v_lshl_add_u64 v[142:143], v[134:135], 0, s[18:19]
	v_lshl_add_u64 v[144:145], s[22:23], 0, v[132:133]
	v_lshl_add_u64 v[146:147], s[22:23], 0, v[134:135]
	v_lshl_add_u64 v[148:149], v[132:133], 0, s[2:3]
	v_lshl_add_u64 v[150:151], v[134:135], 0, s[2:3]
	s_mov_b32 s20, -2
	v_add_u32_e32 v169, v5, v9
	v_add_u32_e32 v165, v2, v1
	v_add_u32_e32 v164, v3, v4
	v_add_u32_e32 v163, v3, v10
	v_add_u32_e32 v162, v3, v11
	v_add_u32_e32 v168, v6, v9
	v_add_u32_e32 v167, v7, v9
	v_add_u32_e32 v166, v8, v9
	s_mov_b64 s[18:19], s[34:35]
	v_mov_b32_e32 v1, v0
	v_mov_b64_e32 v[2:3], v[0:1]
	v_mov_b64_e32 v[4:5], v[0:1]
	v_mov_b64_e32 v[6:7], v[0:1]
	v_mov_b64_e32 v[8:9], v[0:1]
	v_mov_b64_e32 v[10:11], v[0:1]
	v_mov_b64_e32 v[12:13], v[0:1]
	v_mov_b64_e32 v[14:15], v[0:1]
	v_mov_b64_e32 v[16:17], v[0:1]
	v_mov_b64_e32 v[18:19], v[0:1]
	v_mov_b64_e32 v[20:21], v[0:1]
	v_mov_b64_e32 v[22:23], v[0:1]
	v_mov_b64_e32 v[24:25], v[0:1]
	v_mov_b64_e32 v[26:27], v[0:1]
	v_mov_b64_e32 v[28:29], v[0:1]
	v_mov_b64_e32 v[30:31], v[0:1]
	v_mov_b64_e32 v[32:33], v[0:1]
	v_mov_b64_e32 v[34:35], v[0:1]
	v_mov_b64_e32 v[36:37], v[0:1]
	v_mov_b64_e32 v[38:39], v[0:1]
	v_mov_b64_e32 v[40:41], v[0:1]
	v_mov_b64_e32 v[42:43], v[0:1]
	v_mov_b64_e32 v[44:45], v[0:1]
	v_mov_b64_e32 v[46:47], v[0:1]
	v_mov_b64_e32 v[48:49], v[0:1]
	v_mov_b64_e32 v[50:51], v[0:1]
	v_mov_b64_e32 v[52:53], v[0:1]
	v_mov_b64_e32 v[54:55], v[0:1]
	v_mov_b64_e32 v[56:57], v[0:1]
	v_mov_b64_e32 v[58:59], v[0:1]
	v_mov_b64_e32 v[60:61], v[0:1]
	v_mov_b64_e32 v[62:63], v[0:1]
	v_mov_b64_e32 v[64:65], v[0:1]
	v_mov_b64_e32 v[66:67], v[0:1]
	v_mov_b64_e32 v[68:69], v[0:1]
	v_mov_b64_e32 v[70:71], v[0:1]
	v_mov_b64_e32 v[72:73], v[0:1]
	v_mov_b64_e32 v[74:75], v[0:1]
	v_mov_b64_e32 v[76:77], v[0:1]
	v_mov_b64_e32 v[78:79], v[0:1]
	v_mov_b64_e32 v[80:81], v[0:1]
	v_mov_b64_e32 v[82:83], v[0:1]
	v_mov_b64_e32 v[84:85], v[0:1]
	v_mov_b64_e32 v[86:87], v[0:1]
	v_mov_b64_e32 v[88:89], v[0:1]
	v_mov_b64_e32 v[90:91], v[0:1]
	v_mov_b64_e32 v[92:93], v[0:1]
	v_mov_b64_e32 v[94:95], v[0:1]
	v_mov_b64_e32 v[96:97], v[0:1]
	v_mov_b64_e32 v[98:99], v[0:1]
	v_mov_b64_e32 v[100:101], v[0:1]
	v_mov_b64_e32 v[102:103], v[0:1]
	v_mov_b64_e32 v[104:105], v[0:1]
	v_mov_b64_e32 v[106:107], v[0:1]
	v_mov_b64_e32 v[108:109], v[0:1]
	v_mov_b64_e32 v[110:111], v[0:1]
	v_mov_b64_e32 v[112:113], v[0:1]
	v_mov_b64_e32 v[114:115], v[0:1]
	v_mov_b64_e32 v[116:117], v[0:1]
	v_mov_b64_e32 v[118:119], v[0:1]
	v_mov_b64_e32 v[120:121], v[0:1]
	v_mov_b64_e32 v[122:123], v[0:1]
	v_mov_b64_e32 v[124:125], v[0:1]
	v_mov_b64_e32 v[126:127], v[0:1]
